# tile order: QKV GEMM groups of 8 M-tiles x 12 N-tiles (was 4), RKVL GEMM groups of 8 x 14 (was 2): groups align with the 32 tiles an XCD runs per round
# speedup vs baseline: 1.0009x; 1.0009x over previous
.LBB0_526:
	s_andn2_b64 vcc, exec, s[0:1]
	s_cbranch_vccnz .LBB0_850
	v_readlane_b32 s26, v255, 24
	s_cmp_gt_i32 s15, 0
	s_mov_b64 s[0:1], -1
	v_readlane_b32 s27, v255, 25
	s_cbranch_scc0 .LBB0_848
	s_mov_b32 s0, s62
	v_mov_b32_e32 v0, s72
	v_mov_b32_e32 v1, s78
	v_mov_b32_e32 v2, v149
	v_mbcnt_lo_u32_b32 v172, -1, 0
	v_mbcnt_hi_u32_b32 v172, -1, v172
	s_nop 0
	v_readfirstlane_b32 s70, v0
	v_readfirstlane_b32 s71, v1
	v_mov_b32_e32 v0, s52
	v_mov_b32_e32 v1, s53
	v_lshl_add_u32 v183, s0, 6, v172
	v_readfirstlane_b32 s18, v0
	v_readfirstlane_b32 s19, v1
	v_mov_b32_e32 v0, s54
	v_mov_b32_e32 v1, s55
	v_readfirstlane_b32 s0, v2
	v_readfirstlane_b32 s82, v1
	v_ashrrev_i32_e32 v1, 31, v183
	v_lshrrev_b32_e32 v1, 26, v1
	v_add_u32_e32 v1, v183, v1
	v_ashrrev_i32_e32 v173, 6, v1
	v_bfe_i32 v1, v183, 27, 1
	v_readfirstlane_b32 s81, v0
	v_lshlrev_b32_e32 v0, 4, v183
	v_lshrrev_b32_e32 v1, 22, v1
	v_add_u32_e32 v1, v0, v1
	v_and_b32_e32 v1, 0xfffffc00, v1
	v_sub_u32_e32 v1, v0, v1
	v_lshrrev_b32_e32 v2, 4, v1
	v_bitop3_b32 v1, v2, v1, 32 bitop3:0x6c
	v_ashrrev_i32_e32 v3, 31, v1
	v_lshrrev_b32_e32 v3, 26, v3
	v_add_u32_e32 v3, v1, v3
	v_lshlrev_b32_e32 v2, 3, v173
	v_ashrrev_i32_e32 v175, 6, v3
	v_and_b32_e32 v3, 0xc0, v3
	v_and_b32_e32 v2, -16, v2
	v_sub_u32_e32 v1, v1, v3
	v_add_u32_e32 v182, v175, v2
	v_ashrrev_i16_sdwa v1, v151, sext(v1) dst_sel:DWORD dst_unused:UNUSED_PAD src0_sel:DWORD src1_sel:BYTE_0
	v_bfe_i32 v176, v1, 0, 16
	v_lshrrev_b32_e32 v1, 2, v182
	v_and_b32_e32 v1, 4, v1
	v_add_u32_e32 v0, 0x2000, v0
	v_and_or_b32 v186, v175, 3, v1
	v_ashrrev_i32_e32 v1, 31, v0
	v_lshrrev_b32_e32 v1, 22, v1
	v_add_u32_e32 v1, v0, v1
	v_ashrrev_i32_e32 v178, 10, v1
	v_mul_i32_i24_e32 v1, 0x400, v178
	v_sub_u32_e32 v0, v0, v1
	v_lshlrev_b32_e32 v2, 5, v173
	v_lshrrev_b32_e32 v1, 4, v0
	s_add_i32 s80, s0, 0
	v_and_b32_e32 v2, 32, v2
	v_bitop3_b32 v0, v1, v0, 32 bitop3:0x6c
	s_add_u32 s72, s81, 0x600000
	v_add_lshl_u32 v185, v2, v176, 1
	v_ashrrev_i32_e32 v2, 31, v0
	s_addc_u32 s73, s82, 0
	v_lshrrev_b32_e32 v2, 26, v2
	s_add_u32 s0, s81, 0x2800000
	v_add_u32_e32 v2, v0, v2
	s_addc_u32 s1, s82, 0
	v_lshlrev_b32_e32 v1, 3, v178
	v_ashrrev_i32_e32 v179, 6, v2
	v_and_b32_e32 v2, 0xc0, v2
	s_ashr_i32 s74, s71, 31
	v_and_b32_e32 v1, -16, v1
	v_sub_u32_e32 v0, v0, v2
	s_lshr_b32 s2, s74, 29
	v_add_u32_e32 v187, v179, v1
	v_ashrrev_i16_sdwa v0, v151, sext(v0) dst_sel:DWORD dst_unused:UNUSED_PAD src0_sel:DWORD src1_sel:BYTE_0
	s_add_i32 s2, s71, s2
	v_lshlrev_b32_e32 v1, 5, v178
	v_bfe_i32 v180, v0, 0, 16
	v_lshrrev_b32_e32 v0, 2, v187
	s_ashr_i32 s20, s2, 3
	s_and_b32 s2, s2, -8
	v_and_b32_e32 v1, 32, v1
	v_and_b32_e32 v0, 4, v0
	s_sub_i32 s21, s71, s2
	v_and_or_b32 v191, v179, 3, v0
	v_add_lshl_u32 v190, v1, v180, 1
	s_cmp_lt_i32 s21, 0
	v_and_b32_e32 v177, 15, v172
	v_lshlrev_b32_e32 v0, 2, v172
	v_lshlrev_b32_e32 v184, 1, v182
	v_lshl_add_u32 v144, v182, 12, v185
	v_lshlrev_b32_e32 v189, 1, v187
	v_lshl_add_u32 v146, v187, 12, v190
	s_cselect_b64 s[24:25], -1, 0
	s_add_i32 s75, s80, 0x10000
	s_add_i32 s76, s80, 0x14000
	s_add_i32 s77, s80, 0x18000
	s_add_i32 s78, s80, 0x1c000
	s_ashr_i32 s79, s70, 31
	s_ashr_i32 s28, s14, 1
	v_lshlrev_b32_e32 v181, 6, v177
	v_and_b32_e32 v174, 32, v0
	s_andn2_b64 vcc, exec, s[26:27]
	s_mov_b64 s[2:3], -1
	s_cbranch_vccnz .LBB0_696
	s_cmpk_lt_i32 s71, 0x7e0
	s_cselect_b64 s[2:3], -1, 0
	s_add_i32 s4, s80, 0x23eb8
	v_mov_b32_e32 v0, s4
	ds_read2_b32 v[0:1], v0 offset1:1
	s_cmpk_gt_i32 s71, 0x7df
	v_readfirstlane_b32 s6, v183
	s_waitcnt lgkmcnt(0)
	v_readfirstlane_b32 s10, v0
	v_readfirstlane_b32 s11, v1
	s_cbranch_scc1 .LBB0_531
	s_and_b64 s[4:5], s[24:25], exec
	s_movk_i32 s4, 0xfd
	s_cselect_b32 s4, s4, 0xfc
	s_mul_i32 s4, s21, s4
	s_add_i32 s4, s4, s20
	s_mul_hi_i32 s5, s4, 0x92492493
	s_add_i32 s5, s5, s4
	s_lshr_b32 s16, s5, 31
	s_ashr_i32 s5, s5, 6
	s_add_i32 s5, s5, s16
	s_lshl_b32 s16, s5, 3
	s_mul_i32 s5, s5, 112
	s_sub_i32 s4, s4, s5
	s_mov_b32 s5, 0
	s_add_i32 s5, s4, s5
	s_bfe_i32 s17, s5, 0x80000
	s_and_b32 s5, s5, 0xf8
	s_sub_i32 s4, s4, s5
	s_sext_i32_i16 s17, s17
	s_sext_i32_i8 s4, s4
	s_add_i32 s42, s16, s4
	s_ashr_i32 s46, s17, 3

.LBB0_537:
	s_add_i32 s62, s62, 1
	s_mul_i32 s6, s62, s79
	s_mul_hi_u32 s16, s62, s70
	s_add_i32 s6, s16, s6
	s_mul_i32 s16, s62, s70
	s_add_u32 s16, s16, s71
	s_addc_u32 s17, s6, s74
	v_cmp_gt_i64_e32 vcc, s[16:17], v[158:159]
	v_cmp_lt_i64_e64 s[40:41], s[16:17], v[156:157]
	s_cbranch_vccnz .LBB0_539
	s_ashr_i32 s6, s16, 31
	s_lshr_b32 s6, s6, 29
	s_add_i32 s6, s16, s6
	s_ashr_i32 s17, s6, 3
	s_and_b32 s6, s6, -8
	s_sub_i32 s6, s16, s6
	s_cmp_lt_i32 s6, 0
	s_movk_i32 s16, 0xfd
	s_cselect_b32 s16, s16, 0xfc
	s_mul_i32 s6, s6, s16
	s_add_i32 s6, s6, s17
	s_mul_hi_i32 s16, s6, 0x92492493
	s_add_i32 s16, s16, s6
	s_lshr_b32 s17, s16, 31
	s_ashr_i32 s16, s16, 6
	s_add_i32 s16, s16, s17
	s_lshl_b32 s17, s16, 3
	s_sub_i32 s18, 0x90, s17
	s_min_i32 s18, s18, 8
	s_abs_i32 s19, s18
	v_cvt_f32_u32_e32 v0, s19
	s_sub_i32 s21, 0, s19
	s_mul_i32 s16, s16, 112
	s_sub_i32 s6, s6, s16
	v_rcp_iflag_f32_e32 v0, v0
	s_abs_i32 s16, s6
	s_xor_b32 s20, s6, s18
	s_ashr_i32 s20, s20, 31
	v_mul_f32_e32 v0, 0x4f7ffffe, v0
	v_cvt_u32_f32_e32 v0, v0
	s_nop 0
	v_readfirstlane_b32 s30, v0
	s_mul_i32 s21, s21, s30
	s_mul_hi_u32 s21, s30, s21
	s_add_i32 s30, s30, s21
	s_mul_hi_u32 s21, s16, s30
	s_mul_i32 s30, s21, s19
	s_sub_i32 s16, s16, s30
	s_add_i32 s31, s21, 1
	s_sub_i32 s30, s16, s19
	s_cmp_ge_u32 s16, s19
	s_cselect_b32 s21, s31, s21
	s_cselect_b32 s16, s30, s16
	s_add_i32 s30, s21, 1
	s_cmp_ge_u32 s16, s19
	s_cselect_b32 s16, s30, s21
	s_xor_b32 s16, s16, s20
	s_sub_i32 s56, s16, s20
	s_mul_i32 s16, s56, s18
	s_sub_i32 s6, s6, s16
	s_add_i32 s48, s17, s6

.LBB0_696:
	s_and_b64 vcc, exec, s[2:3]
	s_cbranch_vccz .LBB0_847
	s_cmpk_lt_i32 s71, 0x6c0
	s_cselect_b64 s[2:3], -1, 0
	s_add_i32 s5, s80, 0x23ef0
	v_mov_b32_e32 v0, s5
	ds_read2_b32 v[0:1], v0 offset1:1
	s_add_i32 s4, s80, 0x23ef8
	s_cmpk_gt_i32 s71, 0x6bf
	v_readfirstlane_b32 s6, v183
	s_waitcnt lgkmcnt(0)
	v_readfirstlane_b32 s83, v0
	v_mov_b32_e32 v0, s4
	v_readfirstlane_b32 s84, v1
	ds_read2_b32 v[0:1], v0 offset1:1
	s_waitcnt lgkmcnt(0)
	v_readfirstlane_b32 s62, v0
	v_readfirstlane_b32 s85, v1
	s_cbranch_scc1 .LBB0_699
	s_and_b64 s[4:5], s[24:25], exec
	s_movk_i32 s4, 0xd9
	s_cselect_b32 s4, s4, 0xd8
	s_mul_i32 s4, s21, s4
	s_add_i32 s4, s4, s20
	s_mul_hi_i32 s5, s4, 0x2aaaaaab
	s_lshr_b32 s10, s5, 31
	s_ashr_i32 s5, s5, 4
	s_add_i32 s5, s5, s10
	s_lshl_b32 s10, s5, 3
	s_mul_i32 s5, s5, 0x60
	s_sub_i32 s4, s4, s5
	s_bfe_i32 s5, s4, 0x80000
	s_bfe_u32 s5, s5, 0x3000d
	s_add_i32 s5, s4, s5
	s_bfe_i32 s11, s5, 0x80000
	s_and_b32 s5, s5, 0xf8
	s_sub_i32 s4, s4, s5
	s_sext_i32_i16 s11, s11
	s_sext_i32_i8 s4, s4
	s_add_i32 s48, s10, s4
	s_ashr_i32 s64, s11, 3

.LBB0_705:
	s_add_i32 s94, s94, 1
	s_mul_i32 s6, s94, s79
	s_mul_hi_u32 s16, s94, s70
	s_add_i32 s6, s16, s6
	s_mul_i32 s16, s94, s70
	s_add_u32 s16, s16, s71
	s_addc_u32 s17, s6, s74
	v_cmp_gt_i64_e32 vcc, s[16:17], v[162:163]
	v_cmp_lt_i64_e64 s[38:39], s[16:17], v[160:161]
	s_cbranch_vccnz .LBB0_707
	s_ashr_i32 s6, s16, 31
	s_lshr_b32 s6, s6, 29
	s_add_i32 s6, s16, s6
	s_ashr_i32 s17, s6, 3
	s_and_b32 s6, s6, -8
	s_sub_i32 s6, s16, s6
	s_cmp_lt_i32 s6, 0
	s_movk_i32 s16, 0xd9
	s_cselect_b32 s16, s16, 0xd8
	s_mul_i32 s6, s6, s16
	s_add_i32 s6, s6, s17
	s_mul_hi_i32 s16, s6, 0x2aaaaaab
	s_lshr_b32 s17, s16, 31
	s_ashr_i32 s16, s16, 4
	s_add_i32 s16, s16, s17
	s_lshl_b32 s17, s16, 3
	s_sub_i32 s28, 0x90, s17
	s_min_i32 s29, s28, 8
	s_abs_i32 s28, s29
	v_cvt_f32_u32_e32 v0, s28
	s_sub_i32 s43, 0, s28
	s_mul_i32 s16, s16, 0x60
	s_sub_i32 s6, s6, s16
	v_rcp_iflag_f32_e32 v0, v0
	s_abs_i32 s16, s6
	s_xor_b32 s42, s6, s29
	s_ashr_i32 s42, s42, 31
	v_mul_f32_e32 v0, 0x4f7ffffe, v0
	v_cvt_u32_f32_e32 v0, v0
	s_nop 0
	v_readfirstlane_b32 s44, v0
	s_mul_i32 s43, s43, s44
	s_mul_hi_u32 s43, s44, s43
	s_add_i32 s44, s44, s43
	s_mul_hi_u32 s43, s16, s44
	s_mul_i32 s44, s43, s28
	s_sub_i32 s16, s16, s44
	s_add_i32 s45, s43, 1
	s_sub_i32 s44, s16, s28
	s_cmp_ge_u32 s16, s28
	s_cselect_b32 s43, s45, s43
	s_cselect_b32 s16, s44, s16
	s_add_i32 s44, s43, 1
	s_cmp_ge_u32 s16, s28
	s_cselect_b32 s16, s44, s43
	s_xor_b32 s16, s16, s42
	s_sub_i32 s28, s16, s42
	s_mul_i32 s16, s28, s29
	s_sub_i32 s6, s6, s16
	s_add_i32 s42, s17, s6
